# speedup vs baseline: 1.0023x; 1.0023x over previous
; DEV float bf2f(u16 h) { return __uint_as_float(((uint32_t)h) << 16); }
; DEV float opq(float x) { asm volatile("" : "+v"(x)); return x; }
; DEV void ret_out_item(const Params& p, int l, int item, unsigned char* smem) {
;     ...
;     pv_tile(sP, sVt, o, fr, fq);
;   }
;   const float* gw = p.gn_w + l * 512 + h * 128;
;   const size_t tok0 = (size_t)b * SEQ + n * 128 + r0w;
; #pragma unroll
;   for (int mt = 0; mt < MT; ++mt)
; #pragma unroll
;     for (int j = 0; j < 4; ++j) {
;       float sm = 0.f;
; #pragma unroll
;       for (int nt = 0; nt < 8; ++nt) sm = opq(sm + opq(o[mt][nt][j]));
;       sm = grp16_sum(sm);
;       const float mu = opq(sm * (1.0f / 128.0f));
;       float vs = 0.f;
; #pragma unroll
;       for (int nt = 0; nt < 8; ++nt) { const float d = opq(opq(o[mt][nt][j]) - mu); vs = opq(vs + opq(d * d)); }
;       vs = grp16_sum(vs);
;       const float rstd = opq(rsqrtf(opq(vs * (1.0f / 128.0f) + 1e-5f)));
;       const size_t tok = tok0 + mt * 16 + fq * 4 + j;
;       const u16* __restrict__ gp = p.proj + tok * DIN + C_RG + h * 128;
;       u16* __restrict__ op = p.mix + tok * DM + h * 128;
;       float gv[8], wv[8];
; #pragma unroll
;       for (int nt = 0; nt < 8; ++nt) { gv[nt] = bf2f(gp[nt * 16 + fr]); wv[nt] = gw[nt * 16 + fr]; }
.LBB0_340:
	s_or_b64 exec, exec, s[0:1]
	ds_write_b16 v72, v0 offset:528
	s_waitcnt lgkmcnt(0)
	ds_read_b128 v[0:3], v69
	ds_read_b128 v[20:23], v67 offset:62464
	ds_read_b128 v[4:7], v67 offset:53248
	ds_read_b128 v[8:11], v67 offset:55552
	v_add_u32_e32 v24, 0xd000, v67
	ds_read_b128 v[12:15], v67 offset:57856
	ds_read_b128 v[16:19], v67 offset:60160
	v_lshlrev_b32_e32 v128, 1, v90
	s_waitcnt lgkmcnt(3)
	v_mfma_f32_16x16x32_bf16 v[4:7], v[0:3], v[4:7], v[32:35]
	s_lshl_b32 s0, s5, 2
	s_add_u32 s0, s16, s0
	s_addc_u32 s1, s17, 0
	v_mfma_f32_16x16x32_bf16 v[32:35], v[0:3], v[20:23], v[48:51]
	ds_read_b128 v[20:23], v67 offset:64768
	s_add_i32 s4, s4, s33
	s_cmpk_gt_i32 s4, 0x3ff
	s_waitcnt lgkmcnt(3)
	v_mfma_f32_16x16x32_bf16 v[8:11], v[0:3], v[8:11], v[36:39]
	v_add_u32_e32 v48, 0xd040, v67
	s_waitcnt lgkmcnt(0)
	v_mfma_f32_16x16x32_bf16 v[36:39], v[0:3], v[20:23], v[52:55]
	ds_read_b128 v[20:23], v24 offset:13824
	v_mfma_f32_16x16x32_bf16 v[12:15], v[0:3], v[12:15], v[40:43]
	s_waitcnt lgkmcnt(0)
	v_mfma_f32_16x16x32_bf16 v[40:43], v[0:3], v[20:23], v[56:59]
	ds_read_b128 v[20:23], v24 offset:16128
	v_mfma_f32_16x16x32_bf16 v[16:19], v[0:3], v[16:19], v[44:47]
	s_nop 2
	ds_read_b128 v[44:47], v69 offset:64
	s_waitcnt lgkmcnt(1)
	v_mfma_f32_16x16x32_bf16 v[0:3], v[0:3], v[20:23], v[60:63]
	ds_read_b128 v[20:23], v67 offset:53312
	s_waitcnt lgkmcnt(0)
	v_mfma_f32_16x16x32_bf16 v[28:31], v[44:47], v[20:23], v[4:7]
	s_nop 2
	ds_read_b128 v[4:7], v67 offset:55616
	s_waitcnt lgkmcnt(0)
	v_mfma_f32_16x16x32_bf16 v[24:27], v[44:47], v[4:7], v[8:11]
	ds_read_b128 v[4:7], v67 offset:57920
	s_waitcnt lgkmcnt(0)
	v_mfma_f32_16x16x32_bf16 v[20:23], v[44:47], v[4:7], v[12:15]
	ds_read_b128 v[4:7], v67 offset:60224
	s_waitcnt lgkmcnt(0)
	v_mfma_f32_16x16x32_bf16 v[16:19], v[44:47], v[4:7], v[16:19]
	ds_read_b128 v[4:7], v67 offset:62528
	s_waitcnt lgkmcnt(0)
	v_mfma_f32_16x16x32_bf16 v[12:15], v[44:47], v[4:7], v[32:35]
	ds_read_b128 v[4:7], v67 offset:64832
	s_nop 1
	ds_read_b128 v[32:35], v48 offset:16128
	s_waitcnt lgkmcnt(1)
	v_mfma_f32_16x16x32_bf16 v[8:11], v[44:47], v[4:7], v[36:39]
	ds_read_b128 v[4:7], v48 offset:13824
	s_nop 1
	v_mov_b64_e32 v[36:37], s[76:77]
	s_waitcnt lgkmcnt(1)
	v_mfma_f32_16x16x32_bf16 v[0:3], v[44:47], v[32:35], v[0:3]
	v_mov_b32_e32 v32, v28
	v_mov_b32_e32 v33, v24
	v_add_f32_e32 v32, 0, v32
	s_waitcnt lgkmcnt(0)
	v_mfma_f32_16x16x32_bf16 v[4:7], v[44:47], v[4:7], v[40:43]
	v_add_f32_e32 v32, v32, v33
	v_mov_b32_e32 v33, v20
	v_lshl_add_u64 v[34:35], s[6:7], 0, v[80:81]
	v_add_f32_e32 v32, v32, v33
	v_mov_b32_e32 v33, v16
	v_or_b32_e32 v34, v34, v83
	v_add_f32_e32 v32, v32, v33
	v_mov_b32_e32 v33, v12
	v_mul_lo_u32 v41, v35, s88
	v_add_f32_e32 v32, v32, v33
	v_mov_b32_e32 v33, v8
	s_nop 0
	v_add_f32_e32 v32, v32, v33
	v_mov_b32_e32 v33, v4
	s_nop 0
	v_add_f32_e32 v32, v32, v33
	v_mov_b32_e32 v33, v0
	s_nop 0
	v_add_f32_e32 v32, v32, v33
	v_mov_b32_e32 v33, v24
	s_nop 0
	v_add_f32_dpp v32, v32, v32 row_ror:8 row_mask:0xf bank_mask:0xf bound_ctrl:1
	s_nop 1
	v_add_f32_dpp v32, v32, v32 row_ror:4 row_mask:0xf bank_mask:0xf bound_ctrl:1
	s_nop 1
	v_add_f32_dpp v32, v32, v32 row_ror:2 row_mask:0xf bank_mask:0xf bound_ctrl:1
	s_nop 1
	v_add_f32_dpp v32, v32, v32 row_ror:1 row_mask:0xf bank_mask:0xf bound_ctrl:1
	s_nop 0
	v_mul_f32_e32 v42, 0x3c000000, v32
	v_mov_b32_e32 v32, v28
	s_nop 0
	v_sub_f32_e32 v32, v32, v42
	s_nop 0
	v_mul_f32_e32 v32, v32, v32
	s_nop 0
	v_add_f32_e32 v32, 0, v32
	s_nop 0
	v_sub_f32_e32 v33, v33, v42
	s_nop 0
	v_mul_f32_e32 v33, v33, v33
	s_nop 0
	v_add_f32_e32 v32, v32, v33
	v_mov_b32_e32 v33, v20
	s_nop 0
	v_sub_f32_e32 v33, v33, v42
	s_nop 0
	v_mul_f32_e32 v33, v33, v33
	s_nop 0
	v_add_f32_e32 v32, v32, v33
	v_mov_b32_e32 v33, v16
	s_nop 0
	v_sub_f32_e32 v33, v33, v42
	s_nop 0
	v_mul_f32_e32 v33, v33, v33
	s_nop 0
	v_add_f32_e32 v32, v32, v33
	v_mov_b32_e32 v33, v12
	s_nop 0
	v_sub_f32_e32 v33, v33, v42
	s_nop 0
	v_mul_f32_e32 v33, v33, v33
	s_nop 0
	v_add_f32_e32 v32, v32, v33
	v_mov_b32_e32 v33, v8
	s_nop 0
	v_sub_f32_e32 v33, v33, v42
	s_nop 0
	v_mul_f32_e32 v33, v33, v33
	s_nop 0
	v_add_f32_e32 v32, v32, v33
	v_mov_b32_e32 v33, v4
	s_nop 0
	v_sub_f32_e32 v33, v33, v42
	s_nop 0
	v_mul_f32_e32 v33, v33, v33
	s_nop 0
	v_add_f32_e32 v32, v32, v33
	v_mov_b32_e32 v33, v0
	s_nop 0
	v_sub_f32_e32 v33, v33, v42
	s_nop 0
	v_mul_f32_e32 v33, v33, v33
	s_nop 0
	v_add_f32_e32 v32, v32, v33
	s_nop 1
	v_add_f32_dpp v32, v32, v32 row_ror:8 row_mask:0xf bank_mask:0xf bound_ctrl:1
	s_nop 1
	v_add_f32_dpp v32, v32, v32 row_ror:4 row_mask:0xf bank_mask:0xf bound_ctrl:1
	s_nop 1
	v_add_f32_dpp v32, v32, v32 row_ror:2 row_mask:0xf bank_mask:0xf bound_ctrl:1
	s_nop 1
	v_add_f32_dpp v32, v32, v32 row_ror:1 row_mask:0xf bank_mask:0xf bound_ctrl:1
	s_nop 0
	v_fmamk_f32 v32, v32, 0x3c000000, v165
	s_nop 0
	v_cmp_gt_f32_e32 vcc, s84, v32
	v_mul_f32_e32 v33, 0x4b800000, v32
	s_nop 0
	v_cndmask_b32_e32 v32, v32, v33, vcc
	v_rsq_f32_e32 v32, v32
	s_nop 0
	v_mul_f32_e32 v33, 0x45800000, v32
	v_cndmask_b32_e32 v43, v32, v33, vcc
	v_mad_u64_u32 v[32:33], s[6:7], v34, s88, v[36:37]
	v_add_u32_e32 v33, v41, v33
	v_lshl_add_u64 v[38:39], v[32:33], 0, s[18:19]
	v_lshl_add_u64 v[38:39], v[38:39], 0, v[128:129]
	global_load_ushort v200, v[38:39], off offset:3072
	global_load_ushort v201, v[38:39], off offset:3104
	global_load_ushort v202, v[38:39], off offset:3136
	global_load_ushort v203, v[38:39], off offset:3168
	global_load_ushort v204, v[38:39], off offset:3200
	global_load_ushort v205, v[38:39], off offset:3232
	global_load_ushort v206, v[38:39], off offset:3264
	global_load_ushort v207, v[38:39], off offset:3296
	v_lshlrev_b64 v[32:33], 12, v[34:35]
	v_lshl_add_u64 v[48:49], s[78:79], 0, v[32:33]
	v_or_b32_e32 v34, 1, v34
	v_mad_u64_u32 v[36:37], s[6:7], v34, s88, v[36:37]
	v_add_u32_e32 v37, v41, v37
	v_lshl_add_u64 v[36:37], v[36:37], 0, s[18:19]
	v_lshlrev_b64 v[34:35], 12, v[34:35]
	s_waitcnt vmcnt(0)
; DEV float bf2f(u16 h) { return __uint_as_float(((uint32_t)h) << 16); }
; DEV float opq(float x) { asm volatile("" : "+v"(x)); return x; }
; DEV void ret_out_item(const Params& p, int l, int item, unsigned char* smem) {
;     ...
;       float gv[8], wv[8];
; #pragma unroll
;       for (int nt = 0; nt < 8; ++nt) { gv[nt] = bf2f(gp[nt * 16 + fr]); wv[nt] = gw[nt * 16 + fr]; }
; #pragma unroll
;       for (int nt = 0; nt < 8; ++nt) {
;         const float g = gv[nt];
;         const float silu = opq(__fdividef(g, 1.0f + __expf(-g)));
;         const float xn = opq(opq(opq(o[mt][nt][j]) - mu) * rstd);
;         op[nt * 16 + fr] = f2bf(opq(xn * wv[nt]) * silu);
;       }
	v_lshlrev_b32_e32 v50, 16, v200
	v_lshlrev_b32_e32 v40, 2, v90
	global_load_dword v51, v40, s[0:1]
	s_waitcnt vmcnt(0)
	v_lshlrev_b32_e32 v52, 16, v201
	global_load_dword v53, v40, s[0:1] offset:64
	s_waitcnt vmcnt(0)
	v_lshlrev_b32_e32 v54, 16, v202
	global_load_dword v55, v40, s[0:1] offset:128
	s_waitcnt vmcnt(0)
	v_lshlrev_b32_e32 v56, 16, v203
	global_load_dword v57, v40, s[0:1] offset:192
	s_waitcnt vmcnt(0)
	v_lshlrev_b32_e32 v58, 16, v204
	global_load_dword v59, v40, s[0:1] offset:256
	s_waitcnt vmcnt(0)
	v_lshlrev_b32_e32 v60, 16, v205
	global_load_dword v61, v40, s[0:1] offset:320
	global_load_dword v46, v40, s[0:1] offset:384
	s_nop 0
	s_waitcnt vmcnt(2)
	v_lshlrev_b32_e32 v47, 16, v206
	s_waitcnt vmcnt(0)
	v_lshlrev_b32_e32 v45, 16, v207
	v_lshl_add_u64 v[38:39], v[48:49], 0, s[18:19]
	v_mul_f32_e32 v48, 0xbfb8aa3b, v50
	v_exp_f32_e32 v48, v48
	global_load_dword v44, v40, s[0:1] offset:448
	v_lshl_add_u64 v[38:39], v[38:39], 0, v[128:129]
	v_add_f32_e32 v48, 1.0, v48
	v_div_scale_f32 v49, s[6:7], v48, v48, v50
	v_rcp_f32_e32 v62, v49
	s_nop 0
	v_fma_f32 v63, -v49, v62, 1.0
	v_fmac_f32_e32 v62, v63, v62
	v_div_scale_f32 v63, vcc, v50, v48, v50
	v_mul_f32_e32 v64, v63, v62
	v_fma_f32 v65, -v49, v64, v63
	v_fmac_f32_e32 v64, v65, v62
	v_fma_f32 v49, -v49, v64, v63
	v_div_fmas_f32 v49, v49, v62, v64
	v_div_fixup_f32 v48, v49, v48, v50
	s_nop 0
	v_sub_f32_e32 v28, v28, v42
	s_nop 0
	v_mul_f32_e32 v28, v43, v28
	s_nop 0
	v_mul_f32_e32 v28, v51, v28
	s_nop 0
	v_mul_f32_e32 v28, v48, v28
	v_cvt_pk_bf16_f32 v28, v28, s0
	global_store_short v[38:39], v28, off
	v_mul_f32_e32 v28, 0xbfb8aa3b, v52
	v_exp_f32_e32 v28, v28
	s_nop 0
	v_add_f32_e32 v28, 1.0, v28
	v_div_scale_f32 v48, s[6:7], v28, v28, v52
	v_rcp_f32_e32 v49, v48
	s_nop 0
	v_fma_f32 v50, -v48, v49, 1.0
	v_fmac_f32_e32 v49, v50, v49
	v_div_scale_f32 v50, vcc, v52, v28, v52
	v_mul_f32_e32 v51, v50, v49
	v_fma_f32 v62, -v48, v51, v50
	v_fmac_f32_e32 v51, v62, v49
	v_fma_f32 v48, -v48, v51, v50
	v_div_fmas_f32 v48, v48, v49, v51
	v_div_fixup_f32 v28, v48, v28, v52
	s_nop 0
	v_sub_f32_e32 v24, v24, v42
	s_nop 0
	v_mul_f32_e32 v24, v43, v24
	s_nop 0
	v_mul_f32_e32 v24, v53, v24
	s_nop 0
	v_mul_f32_e32 v24, v28, v24
	v_cvt_pk_bf16_f32 v24, v24, s0
	global_store_short v[38:39], v24, off offset:32
	v_mul_f32_e32 v24, 0xbfb8aa3b, v54
	v_exp_f32_e32 v24, v24
	s_nop 0
	v_add_f32_e32 v24, 1.0, v24
	v_div_scale_f32 v28, s[6:7], v24, v24, v54
	v_rcp_f32_e32 v48, v28
	s_nop 0
	v_fma_f32 v49, -v28, v48, 1.0
	v_fmac_f32_e32 v48, v49, v48
	v_div_scale_f32 v49, vcc, v54, v24, v54
	v_mul_f32_e32 v50, v49, v48
	v_fma_f32 v51, -v28, v50, v49
	v_fmac_f32_e32 v50, v51, v48
	v_fma_f32 v28, -v28, v50, v49
	v_div_fmas_f32 v28, v28, v48, v50
	v_div_fixup_f32 v24, v28, v24, v54
	s_nop 0
	v_sub_f32_e32 v20, v20, v42
	s_nop 0
	v_mul_f32_e32 v20, v43, v20
	s_nop 0
	v_mul_f32_e32 v20, v55, v20
	s_nop 0
	v_mul_f32_e32 v20, v24, v20
	v_cvt_pk_bf16_f32 v20, v20, s0
	global_store_short v[38:39], v20, off offset:64
	v_mul_f32_e32 v20, 0xbfb8aa3b, v56
	v_exp_f32_e32 v20, v20
	s_nop 0
	v_add_f32_e32 v20, 1.0, v20
	v_div_scale_f32 v24, s[6:7], v20, v20, v56
	v_rcp_f32_e32 v28, v24
	s_nop 0
	v_fma_f32 v48, -v24, v28, 1.0
	v_fmac_f32_e32 v28, v48, v28
	v_div_scale_f32 v48, vcc, v56, v20, v56
	v_mul_f32_e32 v49, v48, v28
	v_fma_f32 v50, -v24, v49, v48
	v_fmac_f32_e32 v49, v50, v28
	v_fma_f32 v24, -v24, v49, v48
	v_div_fmas_f32 v24, v24, v28, v49
	v_div_fixup_f32 v20, v24, v20, v56
	s_nop 0
	v_sub_f32_e32 v16, v16, v42
	s_nop 0
	v_mul_f32_e32 v16, v43, v16
	s_nop 0
	v_mul_f32_e32 v16, v57, v16
	s_nop 0
	v_mul_f32_e32 v16, v20, v16
	v_cvt_pk_bf16_f32 v16, v16, s0
	global_store_short v[38:39], v16, off offset:96
	v_mul_f32_e32 v16, 0xbfb8aa3b, v58
	v_exp_f32_e32 v16, v16
	s_nop 0
	v_add_f32_e32 v16, 1.0, v16
	v_div_scale_f32 v20, s[6:7], v16, v16, v58
	v_rcp_f32_e32 v24, v20
	s_nop 0
	v_fma_f32 v28, -v20, v24, 1.0
	v_fmac_f32_e32 v24, v28, v24
	v_div_scale_f32 v28, vcc, v58, v16, v58
	v_mul_f32_e32 v48, v28, v24
	v_fma_f32 v49, -v20, v48, v28
	v_fmac_f32_e32 v48, v49, v24
	v_fma_f32 v20, -v20, v48, v28
	v_div_fmas_f32 v20, v20, v24, v48
	v_div_fixup_f32 v16, v20, v16, v58
	s_nop 0
	v_sub_f32_e32 v12, v12, v42
	s_nop 0
	v_mul_f32_e32 v12, v43, v12
	s_nop 0
	v_mul_f32_e32 v12, v59, v12
	s_nop 0
	v_mul_f32_e32 v12, v16, v12
	v_cvt_pk_bf16_f32 v12, v12, s0
	global_store_short v[38:39], v12, off offset:128
	v_mul_f32_e32 v12, 0xbfb8aa3b, v60
	v_exp_f32_e32 v12, v12
	s_nop 0
	v_add_f32_e32 v12, 1.0, v12
	v_div_scale_f32 v16, s[6:7], v12, v12, v60
	v_rcp_f32_e32 v20, v16
	s_nop 0
	v_fma_f32 v24, -v16, v20, 1.0
	v_fmac_f32_e32 v20, v24, v20
	v_div_scale_f32 v24, vcc, v60, v12, v60
	v_mul_f32_e32 v28, v24, v20
	v_fma_f32 v48, -v16, v28, v24
	v_fmac_f32_e32 v28, v48, v20
	v_fma_f32 v16, -v16, v28, v24
	v_div_fmas_f32 v16, v16, v20, v28
	v_div_fixup_f32 v12, v16, v12, v60
	s_nop 0
	v_sub_f32_e32 v8, v8, v42
	s_nop 0
	v_mul_f32_e32 v8, v43, v8
	s_nop 0
	v_mul_f32_e32 v8, v61, v8
	s_nop 0
	v_mul_f32_e32 v8, v12, v8
	v_cvt_pk_bf16_f32 v8, v8, s0
	global_store_short v[38:39], v8, off offset:160
	v_mul_f32_e32 v8, 0xbfb8aa3b, v47
	v_exp_f32_e32 v8, v8
	s_nop 0
	v_add_f32_e32 v8, 1.0, v8
	v_div_scale_f32 v12, s[6:7], v8, v8, v47
	v_rcp_f32_e32 v16, v12
	s_nop 0
	v_fma_f32 v20, -v12, v16, 1.0
	v_fmac_f32_e32 v16, v20, v16
	v_div_scale_f32 v20, vcc, v47, v8, v47
	v_mul_f32_e32 v24, v20, v16
	v_fma_f32 v28, -v12, v24, v20
	v_fmac_f32_e32 v24, v28, v16
	v_fma_f32 v12, -v12, v24, v20
	v_div_fmas_f32 v12, v12, v16, v24
	v_div_fixup_f32 v8, v12, v8, v47
	s_nop 0
	v_sub_f32_e32 v4, v4, v42
	s_nop 0
	v_mul_f32_e32 v4, v43, v4
	s_nop 0
	v_mul_f32_e32 v4, v46, v4
	s_nop 0
	v_mul_f32_e32 v4, v8, v4
	v_cvt_pk_bf16_f32 v4, v4, s0
	global_store_short v[38:39], v4, off offset:192
	v_mul_f32_e32 v4, 0xbfb8aa3b, v45
	v_exp_f32_e32 v4, v4
	s_nop 0
	v_add_f32_e32 v4, 1.0, v4
	v_div_scale_f32 v8, s[6:7], v4, v4, v45
	v_rcp_f32_e32 v12, v8
	s_nop 0
	v_fma_f32 v16, -v8, v12, 1.0
	v_fmac_f32_e32 v12, v16, v12
	v_div_scale_f32 v16, vcc, v45, v4, v45
	v_mul_f32_e32 v20, v16, v12
	v_fma_f32 v24, -v8, v20, v16
	v_fmac_f32_e32 v20, v24, v12
	v_fma_f32 v8, -v8, v20, v16
	v_div_fmas_f32 v8, v8, v12, v20
	v_div_fixup_f32 v4, v8, v4, v45
	v_mov_b32_e32 v8, v25
	v_sub_f32_e32 v0, v0, v42
	s_nop 0
	v_mul_f32_e32 v0, v43, v0
	s_waitcnt vmcnt(7)
; DEV float bf2f(u16 h) { return __uint_as_float(((uint32_t)h) << 16); }
; DEV float opq(float x) { asm volatile("" : "+v"(x)); return x; }
; DEV void ret_out_item(const Params& p, int l, int item, unsigned char* smem) {
;     ...
;     for (int j = 0; j < 4; ++j) {
;       float sm = 0.f;
; #pragma unroll
;       for (int nt = 0; nt < 8; ++nt) sm = opq(sm + opq(o[mt][nt][j]));
;       sm = grp16_sum(sm);
;       const float mu = opq(sm * (1.0f / 128.0f));
;       float vs = 0.f;
; #pragma unroll
;       for (int nt = 0; nt < 8; ++nt) { const float d = opq(opq(o[mt][nt][j]) - mu); vs = opq(vs + opq(d * d)); }
;       vs = grp16_sum(vs);
;       const float rstd = opq(rsqrtf(opq(vs * (1.0f / 128.0f) + 1e-5f)));
;       const size_t tok = tok0 + mt * 16 + fq * 4 + j;
;       const u16* __restrict__ gp = p.proj + tok * DIN + C_RG + h * 128;
;       u16* __restrict__ op = p.mix + tok * DM + h * 128;
;       float gv[8], wv[8];
; #pragma unroll
;       for (int nt = 0; nt < 8; ++nt) { gv[nt] = bf2f(gp[nt * 16 + fr]); wv[nt] = gw[nt * 16 + fr]; }
; #pragma unroll
;       for (int nt = 0; nt < 8; ++nt) {
;         const float g = gv[nt];
;         const float silu = opq(__fdividef(g, 1.0f + __expf(-g)));
;         const float xn = opq(opq(opq(o[mt][nt][j]) - mu) * rstd);
;         op[nt * 16 + fr] = f2bf(opq(xn * wv[nt]) * silu);
;       }
	v_mul_f32_e32 v0, v44, v0
	s_nop 0
	v_mul_f32_e32 v0, v4, v0
	v_cvt_pk_bf16_f32 v0, v0, s0
	global_store_short v[38:39], v0, off offset:224
	v_mov_b32_e32 v0, v29
	v_mov_b32_e32 v4, v25
	v_add_f32_e32 v0, 0, v0
	v_lshl_add_u64 v[38:39], s[78:79], 0, v[34:35]
	v_add_f32_e32 v0, v0, v4
	v_mov_b32_e32 v4, v21
	v_lshl_add_u64 v[34:35], v[36:37], 0, v[128:129]
	v_add_f32_e32 v0, v0, v4
	v_mov_b32_e32 v4, v17
	v_lshl_add_u64 v[36:37], v[38:39], 0, s[18:19]
	v_add_f32_e32 v0, v0, v4
	v_mov_b32_e32 v4, v13
	s_nop 0
	v_add_f32_e32 v0, v0, v4
	v_mov_b32_e32 v4, v9
	s_nop 0
	v_add_f32_e32 v0, v0, v4
	v_mov_b32_e32 v4, v5
	s_nop 0
	v_add_f32_e32 v0, v0, v4
	v_mov_b32_e32 v4, v1
	s_nop 0
	v_add_f32_e32 v0, v0, v4
	v_mov_b32_e32 v4, v29
	s_nop 0
	v_add_f32_dpp v0, v0, v0 row_ror:8 row_mask:0xf bank_mask:0xf bound_ctrl:1
	s_nop 1
	v_add_f32_dpp v0, v0, v0 row_ror:4 row_mask:0xf bank_mask:0xf bound_ctrl:1
	s_nop 1
	v_add_f32_dpp v0, v0, v0 row_ror:2 row_mask:0xf bank_mask:0xf bound_ctrl:1
	s_nop 1
	v_add_f32_dpp v0, v0, v0 row_ror:1 row_mask:0xf bank_mask:0xf bound_ctrl:1
	s_nop 0
	v_mul_f32_e32 v0, 0x3c000000, v0
	s_nop 0
	v_sub_f32_e32 v4, v4, v0
	s_nop 0
	v_mul_f32_e32 v4, v4, v4
	s_nop 0
	v_add_f32_e32 v4, 0, v4
	s_nop 0
	v_sub_f32_e32 v8, v8, v0
	s_nop 0
	v_mul_f32_e32 v8, v8, v8
	s_nop 0
	v_add_f32_e32 v4, v4, v8
	v_mov_b32_e32 v8, v21
	s_nop 0
	v_sub_f32_e32 v8, v8, v0
	s_nop 0
	v_mul_f32_e32 v8, v8, v8
	s_nop 0
	v_add_f32_e32 v4, v4, v8
	v_mov_b32_e32 v8, v17
	s_nop 0
	v_sub_f32_e32 v8, v8, v0
	s_nop 0
	v_mul_f32_e32 v8, v8, v8
	s_nop 0
	v_add_f32_e32 v4, v4, v8
	v_mov_b32_e32 v8, v13
	s_nop 0
	v_sub_f32_e32 v8, v8, v0
	s_nop 0
	v_mul_f32_e32 v8, v8, v8
	s_nop 0
	v_add_f32_e32 v4, v4, v8
	v_mov_b32_e32 v8, v9
	s_nop 0
	v_sub_f32_e32 v8, v8, v0
	s_nop 0
	v_mul_f32_e32 v8, v8, v8
	s_nop 0
	v_add_f32_e32 v4, v4, v8
	v_mov_b32_e32 v8, v5
	s_nop 0
	v_sub_f32_e32 v8, v8, v0
	s_nop 0
	v_mul_f32_e32 v8, v8, v8
	s_nop 0
	v_add_f32_e32 v4, v4, v8
	v_mov_b32_e32 v8, v1
	s_nop 0
	v_sub_f32_e32 v8, v8, v0
	s_nop 0
	v_mul_f32_e32 v8, v8, v8
	s_nop 0
	v_add_f32_e32 v4, v4, v8
	s_nop 1
	v_add_f32_dpp v4, v4, v4 row_ror:8 row_mask:0xf bank_mask:0xf bound_ctrl:1
	s_nop 1
	v_add_f32_dpp v4, v4, v4 row_ror:4 row_mask:0xf bank_mask:0xf bound_ctrl:1
	s_nop 1
	v_add_f32_dpp v4, v4, v4 row_ror:2 row_mask:0xf bank_mask:0xf bound_ctrl:1
	s_nop 1
	v_add_f32_dpp v4, v4, v4 row_ror:1 row_mask:0xf bank_mask:0xf bound_ctrl:1
	s_nop 0
	v_fmamk_f32 v4, v4, 0x3c000000, v165
	s_nop 0
	v_cmp_gt_f32_e32 vcc, s84, v4
	v_mul_f32_e32 v8, 0x4b800000, v4
	s_nop 0
	v_cndmask_b32_e32 v4, v4, v8, vcc
	v_rsq_f32_e32 v4, v4
	s_nop 0
	v_mul_f32_e32 v8, 0x45800000, v4
	v_cndmask_b32_e32 v4, v4, v8, vcc
	global_load_ushort v200, v[34:35], off offset:3072
	global_load_ushort v201, v[34:35], off offset:3104
	global_load_ushort v202, v[34:35], off offset:3136
	global_load_ushort v203, v[34:35], off offset:3168
	global_load_ushort v204, v[34:35], off offset:3200
	global_load_ushort v205, v[34:35], off offset:3232
	global_load_ushort v206, v[34:35], off offset:3264
	global_load_ushort v207, v[34:35], off offset:3296
	s_waitcnt vmcnt(0)
	v_lshlrev_b32_e32 v24, 16, v200
	global_load_dword v28, v40, s[0:1]
	v_mul_f32_e32 v38, 0xbfb8aa3b, v24
	v_exp_f32_e32 v38, v38
	s_waitcnt vmcnt(0)
	v_lshlrev_b32_e32 v41, 16, v201
	global_load_dword v42, v40, s[0:1] offset:64
	v_add_f32_e32 v38, 1.0, v38
	v_div_scale_f32 v39, s[6:7], v38, v38, v24
	v_rcp_f32_e32 v51, v39
	s_waitcnt vmcnt(0)
	v_lshlrev_b32_e32 v43, 16, v202
	global_load_dword v44, v40, s[0:1] offset:128
	v_fma_f32 v52, -v39, v51, 1.0
	v_fmac_f32_e32 v51, v52, v51
	v_div_scale_f32 v52, vcc, v24, v38, v24
	v_mul_f32_e32 v53, v52, v51
	v_fma_f32 v54, -v39, v53, v52
	v_fmac_f32_e32 v53, v54, v51
	v_fma_f32 v39, -v39, v53, v52
	v_div_fmas_f32 v39, v39, v51, v53
	v_div_fixup_f32 v24, v39, v38, v24
	s_waitcnt vmcnt(0)
	v_lshlrev_b32_e32 v45, 16, v203
	global_load_dword v46, v40, s[0:1] offset:192
	s_waitcnt vmcnt(0)
	v_lshlrev_b32_e32 v47, 16, v204
	global_load_dword v48, v40, s[0:1] offset:256
	s_waitcnt vmcnt(0)
	v_lshlrev_b32_e32 v49, 16, v205
	global_load_dword v50, v40, s[0:1] offset:320
	s_waitcnt vmcnt(0)
	v_lshlrev_b32_e32 v20, 16, v206
	global_load_dword v16, v40, s[0:1] offset:384
	s_waitcnt vmcnt(0)
; DEV float bf2f(u16 h) { return __uint_as_float(((uint32_t)h) << 16); }
; DEV float opq(float x) { asm volatile("" : "+v"(x)); return x; }
; DEV void ret_out_item(const Params& p, int l, int item, unsigned char* smem) {
;     ...
; #pragma unroll
;       for (int nt = 0; nt < 8; ++nt) { gv[nt] = bf2f(gp[nt * 16 + fr]); wv[nt] = gw[nt * 16 + fr]; }
; #pragma unroll
;       for (int nt = 0; nt < 8; ++nt) {
;         const float g = gv[nt];
;         const float silu = opq(__fdividef(g, 1.0f + __expf(-g)));
;         const float xn = opq(opq(opq(o[mt][nt][j]) - mu) * rstd);
;         op[nt * 16 + fr] = f2bf(opq(xn * wv[nt]) * silu);
;       }
	v_lshlrev_b32_e32 v12, 16, v207
	global_load_dword v8, v40, s[0:1] offset:448
	s_nop 0
	v_sub_f32_e32 v29, v29, v0
	s_nop 0
	v_mul_f32_e32 v29, v4, v29
	s_nop 0
	v_mul_f32_e32 v28, v28, v29
	s_nop 0
	v_mul_f32_e32 v24, v24, v28
	v_cvt_pk_bf16_f32 v24, v24, s0
	v_lshl_add_u64 v[28:29], v[36:37], 0, v[128:129]
	global_store_short v[28:29], v24, off
	v_mul_f32_e32 v24, 0xbfb8aa3b, v41
	v_exp_f32_e32 v24, v24
	s_nop 0
	v_add_f32_e32 v24, 1.0, v24
	v_div_scale_f32 v36, s[6:7], v24, v24, v41
	v_rcp_f32_e32 v37, v36
	s_nop 0
	v_fma_f32 v38, -v36, v37, 1.0
	v_fmac_f32_e32 v37, v38, v37
	v_div_scale_f32 v38, vcc, v41, v24, v41
	v_mul_f32_e32 v39, v38, v37
	v_fma_f32 v51, -v36, v39, v38
	v_fmac_f32_e32 v39, v51, v37
	v_fma_f32 v36, -v36, v39, v38
	v_div_fmas_f32 v36, v36, v37, v39
	v_div_fixup_f32 v24, v36, v24, v41
	s_nop 0
	v_sub_f32_e32 v25, v25, v0
	s_nop 0
	v_mul_f32_e32 v25, v4, v25
	s_nop 0
	v_mul_f32_e32 v25, v42, v25
	s_nop 0
	v_mul_f32_e32 v24, v24, v25
	v_cvt_pk_bf16_f32 v24, v24, s0
	global_store_short v[28:29], v24, off offset:32
	v_mul_f32_e32 v24, 0xbfb8aa3b, v43
	v_exp_f32_e32 v24, v24
	s_nop 0
	v_add_f32_e32 v24, 1.0, v24
	v_div_scale_f32 v25, s[6:7], v24, v24, v43
	v_rcp_f32_e32 v36, v25
	s_nop 0
	v_fma_f32 v37, -v25, v36, 1.0
	v_fmac_f32_e32 v36, v37, v36
	v_div_scale_f32 v37, vcc, v43, v24, v43
	v_mul_f32_e32 v38, v37, v36
	v_fma_f32 v39, -v25, v38, v37
	v_fmac_f32_e32 v38, v39, v36
	v_fma_f32 v25, -v25, v38, v37
	v_div_fmas_f32 v25, v25, v36, v38
	v_div_fixup_f32 v24, v25, v24, v43
	s_nop 0
	v_sub_f32_e32 v21, v21, v0
	s_nop 0
	v_mul_f32_e32 v21, v4, v21
	s_nop 0
	v_mul_f32_e32 v21, v44, v21
	s_nop 0
	v_mul_f32_e32 v21, v24, v21
	v_cvt_pk_bf16_f32 v21, v21, s0
	global_store_short v[28:29], v21, off offset:64
	v_mul_f32_e32 v21, 0xbfb8aa3b, v45
	v_exp_f32_e32 v21, v21
	s_nop 0
	v_add_f32_e32 v21, 1.0, v21
	v_div_scale_f32 v24, s[6:7], v21, v21, v45
	v_rcp_f32_e32 v25, v24
	s_nop 0
	v_fma_f32 v36, -v24, v25, 1.0
	v_fmac_f32_e32 v25, v36, v25
	v_div_scale_f32 v36, vcc, v45, v21, v45
	v_mul_f32_e32 v37, v36, v25
	v_fma_f32 v38, -v24, v37, v36
	v_fmac_f32_e32 v37, v38, v25
	v_fma_f32 v24, -v24, v37, v36
	v_div_fmas_f32 v24, v24, v25, v37
	v_div_fixup_f32 v21, v24, v21, v45
	s_nop 0
	v_sub_f32_e32 v17, v17, v0
	s_nop 0
	v_mul_f32_e32 v17, v4, v17
	s_nop 0
	v_mul_f32_e32 v17, v46, v17
	s_nop 0
	v_mul_f32_e32 v17, v21, v17
	v_cvt_pk_bf16_f32 v17, v17, s0
	global_store_short v[28:29], v17, off offset:96
	v_mul_f32_e32 v17, 0xbfb8aa3b, v47
	v_exp_f32_e32 v17, v17
	s_nop 0
	v_add_f32_e32 v17, 1.0, v17
	v_div_scale_f32 v21, s[6:7], v17, v17, v47
	v_rcp_f32_e32 v24, v21
	s_nop 0
	v_fma_f32 v25, -v21, v24, 1.0
	v_fmac_f32_e32 v24, v25, v24
	v_div_scale_f32 v25, vcc, v47, v17, v47
	v_mul_f32_e32 v36, v25, v24
	v_fma_f32 v37, -v21, v36, v25
	v_fmac_f32_e32 v36, v37, v24
	v_fma_f32 v21, -v21, v36, v25
	v_div_fmas_f32 v21, v21, v24, v36
	v_div_fixup_f32 v17, v21, v17, v47
	s_nop 0
	v_sub_f32_e32 v13, v13, v0
	s_nop 0
	v_mul_f32_e32 v13, v4, v13
	s_nop 0
	v_mul_f32_e32 v13, v48, v13
	s_nop 0
	v_mul_f32_e32 v13, v17, v13
	v_cvt_pk_bf16_f32 v13, v13, s0
	global_store_short v[28:29], v13, off offset:128
	v_mul_f32_e32 v13, 0xbfb8aa3b, v49
	v_exp_f32_e32 v13, v13
	s_nop 0
	v_add_f32_e32 v13, 1.0, v13
	v_div_scale_f32 v17, s[6:7], v13, v13, v49
	v_rcp_f32_e32 v21, v17
	s_nop 0
	v_fma_f32 v24, -v17, v21, 1.0
	v_fmac_f32_e32 v21, v24, v21
	v_div_scale_f32 v24, vcc, v49, v13, v49
	v_mul_f32_e32 v25, v24, v21
	v_fma_f32 v36, -v17, v25, v24
	v_fmac_f32_e32 v25, v36, v21
	v_fma_f32 v17, -v17, v25, v24
	v_div_fmas_f32 v17, v17, v21, v25
	v_div_fixup_f32 v13, v17, v13, v49
	s_nop 0
	v_sub_f32_e32 v9, v9, v0
	s_nop 0
	v_mul_f32_e32 v9, v4, v9
	s_nop 0
	v_mul_f32_e32 v9, v50, v9
	s_nop 0
	v_mul_f32_e32 v9, v13, v9
	v_cvt_pk_bf16_f32 v9, v9, s0
	global_store_short v[28:29], v9, off offset:160
	v_mul_f32_e32 v9, 0xbfb8aa3b, v20
	v_exp_f32_e32 v9, v9
	s_nop 0
	v_add_f32_e32 v9, 1.0, v9
	v_div_scale_f32 v13, s[6:7], v9, v9, v20
	v_rcp_f32_e32 v17, v13
	s_nop 0
	v_fma_f32 v21, -v13, v17, 1.0
	v_fmac_f32_e32 v17, v21, v17
	v_div_scale_f32 v21, vcc, v20, v9, v20
	v_mul_f32_e32 v24, v21, v17
	v_fma_f32 v25, -v13, v24, v21
	v_fmac_f32_e32 v24, v25, v17
	v_fma_f32 v13, -v13, v24, v21
	v_div_fmas_f32 v13, v13, v17, v24
	v_div_fixup_f32 v9, v13, v9, v20
	s_nop 0
	v_sub_f32_e32 v5, v5, v0
	s_nop 0
	v_mul_f32_e32 v5, v4, v5
	s_nop 0
	v_mul_f32_e32 v5, v16, v5
	s_nop 0
	v_mul_f32_e32 v5, v9, v5
	v_cvt_pk_bf16_f32 v5, v5, s0
	global_store_short v[28:29], v5, off offset:192
	v_mul_f32_e32 v5, 0xbfb8aa3b, v12
	v_exp_f32_e32 v5, v5
	s_nop 0
	v_add_f32_e32 v5, 1.0, v5
	v_div_scale_f32 v9, s[6:7], v5, v5, v12
	v_rcp_f32_e32 v13, v9
	s_mov_b64 s[6:7], 0x2800
	v_fma_f32 v16, -v9, v13, 1.0
	v_fmac_f32_e32 v13, v16, v13
	v_div_scale_f32 v16, vcc, v12, v5, v12
	v_mul_f32_e32 v17, v16, v13
	v_fma_f32 v20, -v9, v17, v16
	v_fmac_f32_e32 v17, v20, v13
	v_fma_f32 v9, -v9, v17, v16
	v_div_fmas_f32 v9, v9, v13, v17
	v_div_fixup_f32 v5, v9, v5, v12
	s_nop 0
	v_sub_f32_e32 v0, v1, v0
	v_mov_b32_e32 v1, v26
	v_mul_f32_e32 v0, v4, v0
	s_waitcnt vmcnt(7)
; DEV float bf2f(u16 h) { return __uint_as_float(((uint32_t)h) << 16); }
; DEV float opq(float x) { asm volatile("" : "+v"(x)); return x; }
; DEV void ret_out_item(const Params& p, int l, int item, unsigned char* smem) {
;     ...
;     for (int j = 0; j < 4; ++j) {
;       float sm = 0.f;
; #pragma unroll
;       for (int nt = 0; nt < 8; ++nt) sm = opq(sm + opq(o[mt][nt][j]));
;       sm = grp16_sum(sm);
;       const float mu = opq(sm * (1.0f / 128.0f));
;       float vs = 0.f;
; #pragma unroll
;       for (int nt = 0; nt < 8; ++nt) { const float d = opq(opq(o[mt][nt][j]) - mu); vs = opq(vs + opq(d * d)); }
;       vs = grp16_sum(vs);
;       const float rstd = opq(rsqrtf(opq(vs * (1.0f / 128.0f) + 1e-5f)));
;       const size_t tok = tok0 + mt * 16 + fq * 4 + j;
;       const u16* __restrict__ gp = p.proj + tok * DIN + C_RG + h * 128;
;       u16* __restrict__ op = p.mix + tok * DM + h * 128;
;       float gv[8], wv[8];
; #pragma unroll
;       for (int nt = 0; nt < 8; ++nt) { gv[nt] = bf2f(gp[nt * 16 + fr]); wv[nt] = gw[nt * 16 + fr]; }
; #pragma unroll
;       for (int nt = 0; nt < 8; ++nt) {
;         const float g = gv[nt];
;         const float silu = opq(__fdividef(g, 1.0f + __expf(-g)));
;         const float xn = opq(opq(opq(o[mt][nt][j]) - mu) * rstd);
;         op[nt * 16 + fr] = f2bf(opq(xn * wv[nt]) * silu);
;       }
	v_mul_f32_e32 v0, v8, v0
	v_lshl_add_u64 v[8:9], v[34:35], 0, s[6:7]
	v_mul_f32_e32 v0, v5, v0
	v_cvt_pk_bf16_f32 v0, v0, s0
	global_store_short v[28:29], v0, off offset:224
	v_mov_b32_e32 v0, v30
	s_nop 0
	v_add_f32_e32 v0, 0, v0
	s_nop 0
	v_add_f32_e32 v0, v0, v1
	v_mov_b32_e32 v1, v22
	s_nop 0
	v_add_f32_e32 v0, v0, v1
	v_mov_b32_e32 v1, v18
	s_nop 0
	v_add_f32_e32 v0, v0, v1
	v_mov_b32_e32 v1, v14
	s_nop 0
	v_add_f32_e32 v0, v0, v1
	v_mov_b32_e32 v1, v10
	s_nop 0
	v_add_f32_e32 v0, v0, v1
	v_mov_b32_e32 v1, v6
	s_nop 0
	v_add_f32_e32 v0, v0, v1
	v_mov_b32_e32 v1, v2
	s_nop 0
	v_add_f32_e32 v0, v0, v1
	v_mov_b32_e32 v1, v26
	s_nop 0
	v_add_f32_dpp v0, v0, v0 row_ror:8 row_mask:0xf bank_mask:0xf bound_ctrl:1
	s_nop 1
	v_add_f32_dpp v0, v0, v0 row_ror:4 row_mask:0xf bank_mask:0xf bound_ctrl:1
	s_nop 1
	v_add_f32_dpp v0, v0, v0 row_ror:2 row_mask:0xf bank_mask:0xf bound_ctrl:1
	s_nop 1
	v_add_f32_dpp v0, v0, v0 row_ror:1 row_mask:0xf bank_mask:0xf bound_ctrl:1
	s_nop 0
	v_mul_f32_e32 v4, 0x3c000000, v0
	v_mov_b32_e32 v0, v30
	s_nop 0
	v_sub_f32_e32 v0, v0, v4
	s_nop 0
	v_mul_f32_e32 v0, v0, v0
	s_nop 0
	v_add_f32_e32 v0, 0, v0
	s_nop 0
	v_sub_f32_e32 v1, v1, v4
	s_nop 0
	v_mul_f32_e32 v1, v1, v1
	s_nop 0
	v_add_f32_e32 v0, v0, v1
	v_mov_b32_e32 v1, v22
	s_nop 0
	v_sub_f32_e32 v1, v1, v4
	s_nop 0
	v_mul_f32_e32 v1, v1, v1
	s_nop 0
	v_add_f32_e32 v0, v0, v1
	v_mov_b32_e32 v1, v18
	s_nop 0
	v_sub_f32_e32 v1, v1, v4
	s_nop 0
	v_mul_f32_e32 v1, v1, v1
	s_nop 0
	v_add_f32_e32 v0, v0, v1
	v_mov_b32_e32 v1, v14
	s_nop 0
	v_sub_f32_e32 v1, v1, v4
	s_nop 0
	v_mul_f32_e32 v1, v1, v1
	s_nop 0
	v_add_f32_e32 v0, v0, v1
	v_mov_b32_e32 v1, v10
	s_nop 0
	v_sub_f32_e32 v1, v1, v4
	s_nop 0
	v_mul_f32_e32 v1, v1, v1
	s_nop 0
	v_add_f32_e32 v0, v0, v1
	v_mov_b32_e32 v1, v6
	s_nop 0
	v_sub_f32_e32 v1, v1, v4
	s_nop 0
	v_mul_f32_e32 v1, v1, v1
	s_nop 0
	v_add_f32_e32 v0, v0, v1
	v_mov_b32_e32 v1, v2
	s_nop 0
	v_sub_f32_e32 v1, v1, v4
	s_nop 0
	v_mul_f32_e32 v1, v1, v1
	s_nop 0
	v_add_f32_e32 v0, v0, v1
	s_nop 1
	v_add_f32_dpp v0, v0, v0 row_ror:8 row_mask:0xf bank_mask:0xf bound_ctrl:1
	s_nop 1
	v_add_f32_dpp v0, v0, v0 row_ror:4 row_mask:0xf bank_mask:0xf bound_ctrl:1
	s_nop 1
	v_add_f32_dpp v0, v0, v0 row_ror:2 row_mask:0xf bank_mask:0xf bound_ctrl:1
	s_nop 1
	v_add_f32_dpp v0, v0, v0 row_ror:1 row_mask:0xf bank_mask:0xf bound_ctrl:1
	s_nop 0
	v_fmamk_f32 v0, v0, 0x3c000000, v165
	s_nop 0
	v_cmp_gt_f32_e32 vcc, s84, v0
	v_mul_f32_e32 v1, 0x4b800000, v0
	s_nop 0
	v_cndmask_b32_e32 v0, v0, v1, vcc
	v_rsq_f32_e32 v0, v0
	s_nop 0
	v_mul_f32_e32 v1, 0x45800000, v0
	v_cndmask_b32_e32 v5, v0, v1, vcc
	global_load_ushort v200, v[8:9], off offset:3072
	global_load_ushort v201, v[8:9], off offset:3104
	global_load_ushort v202, v[8:9], off offset:3136
	global_load_ushort v203, v[8:9], off offset:3168
	global_load_ushort v204, v[8:9], off offset:3200
	global_load_ushort v205, v[8:9], off offset:3232
	global_load_ushort v206, v[8:9], off offset:3264
	global_load_ushort v207, v[8:9], off offset:3296
	v_or_b32_e32 v0, 0x2000, v32
	v_mov_b32_e32 v1, v33
	v_lshl_add_u64 v[0:1], s[78:79], 0, v[0:1]
	v_lshl_add_u64 v[0:1], v[0:1], 0, s[18:19]
	v_lshl_add_u64 v[0:1], v[0:1], 0, v[128:129]
	v_or_b32_e32 v32, 0x3000, v32
	s_waitcnt vmcnt(0)
	v_lshlrev_b32_e32 v16, 16, v200
	global_load_dword v17, v40, s[0:1]
	v_mul_f32_e32 v41, 0xbfb8aa3b, v16
	v_exp_f32_e32 v41, v41
	s_waitcnt vmcnt(0)
	v_lshlrev_b32_e32 v20, 16, v201
	global_load_dword v21, v40, s[0:1] offset:64
	v_add_f32_e32 v41, 1.0, v41
	v_div_scale_f32 v42, s[6:7], v41, v41, v16
	v_rcp_f32_e32 v43, v42
	s_waitcnt vmcnt(0)
	v_lshlrev_b32_e32 v24, 16, v202
	global_load_dword v25, v40, s[0:1] offset:128
	v_fma_f32 v44, -v42, v43, 1.0
	v_fmac_f32_e32 v43, v44, v43
	v_div_scale_f32 v44, vcc, v16, v41, v16
	v_mul_f32_e32 v45, v44, v43
	v_fma_f32 v46, -v42, v45, v44
	v_fmac_f32_e32 v45, v46, v43
	v_fma_f32 v42, -v42, v45, v44
	v_div_fmas_f32 v42, v42, v43, v45
	v_div_fixup_f32 v16, v42, v41, v16
	s_waitcnt vmcnt(0)
	v_lshlrev_b32_e32 v28, 16, v203
	global_load_dword v29, v40, s[0:1] offset:192
	s_waitcnt vmcnt(0)
	v_lshlrev_b32_e32 v36, 16, v204
	global_load_dword v37, v40, s[0:1] offset:256
	s_waitcnt vmcnt(0)
	v_lshlrev_b32_e32 v38, 16, v205
	global_load_dword v39, v40, s[0:1] offset:320
	s_waitcnt vmcnt(0)
	v_lshlrev_b32_e32 v13, 16, v206
	global_load_dword v12, v40, s[0:1] offset:384
	s_nop 0
	s_waitcnt vmcnt(0)
; DEV float bf2f(u16 h) { return __uint_as_float(((uint32_t)h) << 16); }
; DEV float opq(float x) { asm volatile("" : "+v"(x)); return x; }
; DEV void ret_out_item(const Params& p, int l, int item, unsigned char* smem) {
;     ...
; #pragma unroll
;       for (int nt = 0; nt < 8; ++nt) { gv[nt] = bf2f(gp[nt * 16 + fr]); wv[nt] = gw[nt * 16 + fr]; }
; #pragma unroll
;       for (int nt = 0; nt < 8; ++nt) {
;         const float g = gv[nt];
;         const float silu = opq(__fdividef(g, 1.0f + __expf(-g)));
;         const float xn = opq(opq(opq(o[mt][nt][j]) - mu) * rstd);
;         op[nt * 16 + fr] = f2bf(opq(xn * wv[nt]) * silu);
;       }
	v_lshlrev_b32_e32 v9, 16, v207
	global_load_dword v8, v40, s[0:1] offset:448
	s_nop 0
	v_sub_f32_e32 v30, v30, v4
	s_nop 0
	v_mul_f32_e32 v30, v5, v30
	s_nop 0
	v_mul_f32_e32 v17, v17, v30
	s_nop 0
	v_mul_f32_e32 v16, v16, v17
	v_cvt_pk_bf16_f32 v16, v16, s0
	global_store_short v[0:1], v16, off
	v_mul_f32_e32 v16, 0xbfb8aa3b, v20
	v_exp_f32_e32 v16, v16
	s_nop 0
	v_add_f32_e32 v16, 1.0, v16
	v_div_scale_f32 v17, s[6:7], v16, v16, v20
	v_rcp_f32_e32 v30, v17
	s_nop 0
	v_fma_f32 v41, -v17, v30, 1.0
	v_fmac_f32_e32 v30, v41, v30
	v_div_scale_f32 v41, vcc, v20, v16, v20
	v_mul_f32_e32 v42, v41, v30
	v_fma_f32 v43, -v17, v42, v41
	v_fmac_f32_e32 v42, v43, v30
	v_fma_f32 v17, -v17, v42, v41
	v_div_fmas_f32 v17, v17, v30, v42
	v_div_fixup_f32 v16, v17, v16, v20
	s_nop 0
	v_sub_f32_e32 v17, v26, v4
	s_nop 0
	v_mul_f32_e32 v17, v5, v17
	s_nop 0
	v_mul_f32_e32 v17, v21, v17
	s_nop 0
	v_mul_f32_e32 v16, v16, v17
	v_cvt_pk_bf16_f32 v16, v16, s0
	global_store_short v[0:1], v16, off offset:32
	v_mul_f32_e32 v16, 0xbfb8aa3b, v24
	v_exp_f32_e32 v16, v16
	s_nop 0
	v_add_f32_e32 v16, 1.0, v16
	v_div_scale_f32 v17, s[6:7], v16, v16, v24
	v_rcp_f32_e32 v20, v17
	s_nop 0
	v_fma_f32 v21, -v17, v20, 1.0
	v_fmac_f32_e32 v20, v21, v20
	v_div_scale_f32 v21, vcc, v24, v16, v24
	v_mul_f32_e32 v26, v21, v20
	v_fma_f32 v30, -v17, v26, v21
	v_fmac_f32_e32 v26, v30, v20
	v_fma_f32 v17, -v17, v26, v21
	v_div_fmas_f32 v17, v17, v20, v26
	v_div_fixup_f32 v16, v17, v16, v24
	s_nop 0
	v_sub_f32_e32 v17, v22, v4
	s_nop 0
	v_mul_f32_e32 v17, v5, v17
	s_nop 0
	v_mul_f32_e32 v17, v25, v17
	s_nop 0
	v_mul_f32_e32 v16, v16, v17
	v_cvt_pk_bf16_f32 v16, v16, s0
	global_store_short v[0:1], v16, off offset:64
	v_mul_f32_e32 v16, 0xbfb8aa3b, v28
	v_exp_f32_e32 v16, v16
	s_nop 0
	v_add_f32_e32 v16, 1.0, v16
	v_div_scale_f32 v17, s[6:7], v16, v16, v28
	v_rcp_f32_e32 v20, v17
	s_nop 0
	v_fma_f32 v21, -v17, v20, 1.0
	v_fmac_f32_e32 v20, v21, v20
	v_div_scale_f32 v21, vcc, v28, v16, v28
	v_mul_f32_e32 v22, v21, v20
	v_fma_f32 v24, -v17, v22, v21
	v_fmac_f32_e32 v22, v24, v20
	v_fma_f32 v17, -v17, v22, v21
	v_div_fmas_f32 v17, v17, v20, v22
	v_div_fixup_f32 v16, v17, v16, v28
	s_nop 0
	v_sub_f32_e32 v17, v18, v4
	s_nop 0
	v_mul_f32_e32 v17, v5, v17
	s_nop 0
	v_mul_f32_e32 v17, v29, v17
	s_nop 0
	v_mul_f32_e32 v16, v16, v17
	v_cvt_pk_bf16_f32 v16, v16, s0
	global_store_short v[0:1], v16, off offset:96
	v_mul_f32_e32 v16, 0xbfb8aa3b, v36
	v_exp_f32_e32 v16, v16
	s_nop 0
	v_add_f32_e32 v16, 1.0, v16
	v_div_scale_f32 v17, s[6:7], v16, v16, v36
	v_rcp_f32_e32 v18, v17
	s_nop 0
	v_fma_f32 v20, -v17, v18, 1.0
	v_fmac_f32_e32 v18, v20, v18
	v_div_scale_f32 v20, vcc, v36, v16, v36
	v_mul_f32_e32 v21, v20, v18
	v_fma_f32 v22, -v17, v21, v20
	v_fmac_f32_e32 v21, v22, v18
	v_fma_f32 v17, -v17, v21, v20
	v_div_fmas_f32 v17, v17, v18, v21
	v_div_fixup_f32 v16, v17, v16, v36
	s_nop 0
	v_sub_f32_e32 v14, v14, v4
	s_nop 0
	v_mul_f32_e32 v14, v5, v14
	s_nop 0
	v_mul_f32_e32 v14, v37, v14
	s_nop 0
	v_mul_f32_e32 v14, v16, v14
	v_cvt_pk_bf16_f32 v14, v14, s0
	global_store_short v[0:1], v14, off offset:128
	v_mul_f32_e32 v14, 0xbfb8aa3b, v38
	v_exp_f32_e32 v14, v14
	s_nop 0
	v_add_f32_e32 v14, 1.0, v14
	v_div_scale_f32 v16, s[6:7], v14, v14, v38
	v_rcp_f32_e32 v17, v16
	s_nop 0
	v_fma_f32 v18, -v16, v17, 1.0
	v_fmac_f32_e32 v17, v18, v17
	v_div_scale_f32 v18, vcc, v38, v14, v38
	v_mul_f32_e32 v20, v18, v17
	v_fma_f32 v21, -v16, v20, v18
	v_fmac_f32_e32 v20, v21, v17
	v_fma_f32 v16, -v16, v20, v18
	v_div_fmas_f32 v16, v16, v17, v20
	v_div_fixup_f32 v14, v16, v14, v38
	s_nop 0
	v_sub_f32_e32 v10, v10, v4
	s_nop 0
	v_mul_f32_e32 v10, v5, v10
	s_nop 0
	v_mul_f32_e32 v10, v39, v10
	s_nop 0
	v_mul_f32_e32 v10, v14, v10
	v_cvt_pk_bf16_f32 v10, v10, s0
	global_store_short v[0:1], v10, off offset:160
	v_mul_f32_e32 v10, 0xbfb8aa3b, v13
	v_exp_f32_e32 v10, v10
	s_nop 0
	v_add_f32_e32 v10, 1.0, v10
	v_div_scale_f32 v14, s[6:7], v10, v10, v13
	v_rcp_f32_e32 v16, v14
	s_nop 0
	v_fma_f32 v17, -v14, v16, 1.0
	v_fmac_f32_e32 v16, v17, v16
	v_div_scale_f32 v17, vcc, v13, v10, v13
	v_mul_f32_e32 v18, v17, v16
	v_fma_f32 v20, -v14, v18, v17
	v_fmac_f32_e32 v18, v20, v16
	v_fma_f32 v14, -v14, v18, v17
	v_div_fmas_f32 v14, v14, v16, v18
	v_div_fixup_f32 v10, v14, v10, v13
	s_nop 0
	v_sub_f32_e32 v6, v6, v4
	s_nop 0
	v_mul_f32_e32 v6, v5, v6
	s_nop 0
	v_mul_f32_e32 v6, v12, v6
	s_nop 0
	v_mul_f32_e32 v6, v10, v6
	v_cvt_pk_bf16_f32 v6, v6, s0
	global_store_short v[0:1], v6, off offset:192
	v_mul_f32_e32 v6, 0xbfb8aa3b, v9
	v_exp_f32_e32 v6, v6
	s_nop 0
	v_add_f32_e32 v6, 1.0, v6
	v_div_scale_f32 v10, s[6:7], v6, v6, v9
	v_rcp_f32_e32 v12, v10
	s_mov_b64 s[6:7], 0x5000
	v_fma_f32 v13, -v10, v12, 1.0
	v_fmac_f32_e32 v12, v13, v12
	v_div_scale_f32 v13, vcc, v9, v6, v9
	v_mul_f32_e32 v14, v13, v12
	v_fma_f32 v16, -v10, v14, v13
	v_fmac_f32_e32 v14, v16, v12
	v_fma_f32 v10, -v10, v14, v13
	v_div_fmas_f32 v10, v10, v12, v14
	v_div_fixup_f32 v6, v10, v6, v9
	v_lshl_add_u64 v[12:13], v[34:35], 0, s[6:7]
	v_sub_f32_e32 v2, v2, v4
	s_nop 0
	v_mul_f32_e32 v2, v5, v2
	s_waitcnt vmcnt(7)
; DEV float bf2f(u16 h) { return __uint_as_float(((uint32_t)h) << 16); }
; DEV float opq(float x) { asm volatile("" : "+v"(x)); return x; }
; DEV void ret_out_item(const Params& p, int l, int item, unsigned char* smem) {
;     ...
;     for (int j = 0; j < 4; ++j) {
;       float sm = 0.f;
; #pragma unroll
;       for (int nt = 0; nt < 8; ++nt) sm = opq(sm + opq(o[mt][nt][j]));
;       sm = grp16_sum(sm);
;       const float mu = opq(sm * (1.0f / 128.0f));
;       float vs = 0.f;
; #pragma unroll
;       for (int nt = 0; nt < 8; ++nt) { const float d = opq(opq(o[mt][nt][j]) - mu); vs = opq(vs + opq(d * d)); }
;       vs = grp16_sum(vs);
;       const float rstd = opq(rsqrtf(opq(vs * (1.0f / 128.0f) + 1e-5f)));
;       const size_t tok = tok0 + mt * 16 + fq * 4 + j;
;       const u16* __restrict__ gp = p.proj + tok * DIN + C_RG + h * 128;
;       u16* __restrict__ op = p.mix + tok * DM + h * 128;
;       float gv[8], wv[8];
; #pragma unroll
;       for (int nt = 0; nt < 8; ++nt) { gv[nt] = bf2f(gp[nt * 16 + fr]); wv[nt] = gw[nt * 16 + fr]; }
; #pragma unroll
;       for (int nt = 0; nt < 8; ++nt) {
;         const float g = gv[nt];
;         const float silu = opq(__fdividef(g, 1.0f + __expf(-g)));
;         const float xn = opq(opq(opq(o[mt][nt][j]) - mu) * rstd);
;         op[nt * 16 + fr] = f2bf(opq(xn * wv[nt]) * silu);
;       }
	v_mul_f32_e32 v2, v8, v2
	s_nop 0
	v_mul_f32_e32 v2, v6, v2
	v_cvt_pk_bf16_f32 v2, v2, s0
	global_store_short v[0:1], v2, off offset:224
	v_mov_b32_e32 v0, v31
	v_mov_b32_e32 v1, v27
	v_add_f32_e32 v0, 0, v0
	s_nop 0
	v_add_f32_e32 v0, v0, v1
	v_mov_b32_e32 v1, v23
	s_nop 0
	v_add_f32_e32 v0, v0, v1
	v_mov_b32_e32 v1, v19
	s_nop 0
	v_add_f32_e32 v0, v0, v1
	v_mov_b32_e32 v1, v15
	s_nop 0
	v_add_f32_e32 v0, v0, v1
	v_mov_b32_e32 v1, v11
	s_nop 0
	v_add_f32_e32 v0, v0, v1
	v_mov_b32_e32 v1, v7
	s_nop 0
	v_add_f32_e32 v0, v0, v1
	v_mov_b32_e32 v1, v3
	s_nop 0
	v_add_f32_e32 v0, v0, v1
	v_mov_b32_e32 v1, v27
	s_nop 0
	v_add_f32_dpp v0, v0, v0 row_ror:8 row_mask:0xf bank_mask:0xf bound_ctrl:1
	s_nop 1
	v_add_f32_dpp v0, v0, v0 row_ror:4 row_mask:0xf bank_mask:0xf bound_ctrl:1
	s_nop 1
	v_add_f32_dpp v0, v0, v0 row_ror:2 row_mask:0xf bank_mask:0xf bound_ctrl:1
	s_nop 1
	v_add_f32_dpp v0, v0, v0 row_ror:1 row_mask:0xf bank_mask:0xf bound_ctrl:1
	s_nop 0
	v_mul_f32_e32 v2, 0x3c000000, v0
	v_mov_b32_e32 v0, v31
	s_nop 0
	v_sub_f32_e32 v0, v0, v2
	s_nop 0
	v_mul_f32_e32 v0, v0, v0
	s_nop 0
	v_add_f32_e32 v0, 0, v0
	s_nop 0
	v_sub_f32_e32 v1, v1, v2
	s_nop 0
	v_mul_f32_e32 v1, v1, v1
	s_nop 0
	v_add_f32_e32 v0, v0, v1
	v_mov_b32_e32 v1, v23
	s_nop 0
	v_sub_f32_e32 v1, v1, v2
	s_nop 0
	v_mul_f32_e32 v1, v1, v1
	s_nop 0
	v_add_f32_e32 v0, v0, v1
	v_mov_b32_e32 v1, v19
	s_nop 0
	v_sub_f32_e32 v1, v1, v2
	s_nop 0
	v_mul_f32_e32 v1, v1, v1
	s_nop 0
	v_add_f32_e32 v0, v0, v1
	v_mov_b32_e32 v1, v15
	s_nop 0
	v_sub_f32_e32 v1, v1, v2
	s_nop 0
	v_mul_f32_e32 v1, v1, v1
	s_nop 0
	v_add_f32_e32 v0, v0, v1
	v_mov_b32_e32 v1, v11
	s_nop 0
	v_sub_f32_e32 v1, v1, v2
	s_nop 0
	v_mul_f32_e32 v1, v1, v1
	s_nop 0
	v_add_f32_e32 v0, v0, v1
	v_mov_b32_e32 v1, v7
	s_nop 0
	v_sub_f32_e32 v1, v1, v2
	s_nop 0
	v_mul_f32_e32 v1, v1, v1
	s_nop 0
	v_add_f32_e32 v0, v0, v1
	v_mov_b32_e32 v1, v3
	s_nop 0
	v_sub_f32_e32 v1, v1, v2
	s_nop 0
	v_mul_f32_e32 v1, v1, v1
	s_nop 0
	v_add_f32_e32 v0, v0, v1
	s_nop 1
	v_add_f32_dpp v0, v0, v0 row_ror:8 row_mask:0xf bank_mask:0xf bound_ctrl:1
	s_nop 1
	v_add_f32_dpp v0, v0, v0 row_ror:4 row_mask:0xf bank_mask:0xf bound_ctrl:1
	s_nop 1
	v_add_f32_dpp v0, v0, v0 row_ror:2 row_mask:0xf bank_mask:0xf bound_ctrl:1
	s_nop 1
	v_add_f32_dpp v0, v0, v0 row_ror:1 row_mask:0xf bank_mask:0xf bound_ctrl:1
	s_nop 0
	v_fmamk_f32 v0, v0, 0x3c000000, v165
	s_nop 0
	v_cmp_gt_f32_e32 vcc, s84, v0
	v_mul_f32_e32 v1, 0x4b800000, v0
	s_nop 0
	v_cndmask_b32_e32 v0, v0, v1, vcc
	v_rsq_f32_e32 v0, v0
	s_nop 0
	v_mul_f32_e32 v1, 0x45800000, v0
	v_cndmask_b32_e32 v4, v0, v1, vcc
	global_load_ushort v200, v[12:13], off offset:3072
	global_load_ushort v201, v[12:13], off offset:3104
	global_load_ushort v202, v[12:13], off offset:3136
	global_load_ushort v203, v[12:13], off offset:3168
	global_load_ushort v204, v[12:13], off offset:3200
	global_load_ushort v205, v[12:13], off offset:3232
	global_load_ushort v206, v[12:13], off offset:3264
	global_load_ushort v207, v[12:13], off offset:3296
	v_lshl_add_u64 v[0:1], s[78:79], 0, v[32:33]
	v_lshl_add_u64 v[0:1], v[0:1], 0, s[18:19]
	v_lshl_add_u64 v[0:1], v[0:1], 0, v[128:129]
	s_waitcnt vmcnt(0)
	v_lshlrev_b32_e32 v10, 16, v200
	global_load_dword v14, v40, s[0:1]
	s_waitcnt vmcnt(0)
	v_lshlrev_b32_e32 v16, 16, v201
	global_load_dword v17, v40, s[0:1] offset:64
	s_waitcnt vmcnt(0)
	v_lshlrev_b32_e32 v18, 16, v202
	global_load_dword v20, v40, s[0:1] offset:128
	s_waitcnt vmcnt(0)
	v_lshlrev_b32_e32 v21, 16, v203
	global_load_dword v22, v40, s[0:1] offset:192
	s_waitcnt vmcnt(0)
	v_lshlrev_b32_e32 v24, 16, v204
	global_load_dword v25, v40, s[0:1] offset:256
	s_waitcnt vmcnt(0)
	v_lshlrev_b32_e32 v26, 16, v205
	global_load_dword v28, v40, s[0:1] offset:320
	s_waitcnt vmcnt(0)
	v_lshlrev_b32_e32 v9, 16, v206
	global_load_dword v8, v40, s[0:1] offset:384
	v_mul_f32_e32 v12, 0xbfb8aa3b, v10
	v_exp_f32_e32 v12, v12
	s_waitcnt vmcnt(0)
; DEV float bf2f(u16 h) { return __uint_as_float(((uint32_t)h) << 16); }
; DEV float opq(float x) { asm volatile("" : "+v"(x)); return x; }
; DEV void ret_out_item(const Params& p, int l, int item, unsigned char* smem) {
;     ...
; #pragma unroll
;       for (int nt = 0; nt < 8; ++nt) { gv[nt] = bf2f(gp[nt * 16 + fr]); wv[nt] = gw[nt * 16 + fr]; }
; #pragma unroll
;       for (int nt = 0; nt < 8; ++nt) {
;         const float g = gv[nt];
;         const float silu = opq(__fdividef(g, 1.0f + __expf(-g)));
;         const float xn = opq(opq(opq(o[mt][nt][j]) - mu) * rstd);
;         op[nt * 16 + fr] = f2bf(opq(xn * wv[nt]) * silu);
;       }
	v_lshlrev_b32_e32 v6, 16, v207
	v_add_f32_e32 v12, 1.0, v12
	global_load_dword v5, v40, s[0:1] offset:448
	v_div_scale_f32 v13, s[0:1], v12, v12, v10
	v_rcp_f32_e32 v29, v13
	s_nop 0
	v_fma_f32 v30, -v13, v29, 1.0
	v_fmac_f32_e32 v29, v30, v29
	v_div_scale_f32 v30, vcc, v10, v12, v10
	v_mul_f32_e32 v32, v30, v29
	v_fma_f32 v33, -v13, v32, v30
	v_fmac_f32_e32 v32, v33, v29
	v_fma_f32 v13, -v13, v32, v30
	v_div_fmas_f32 v13, v13, v29, v32
	v_div_fixup_f32 v10, v13, v12, v10
	s_nop 0
	v_sub_f32_e32 v12, v31, v2
	s_nop 0
	v_mul_f32_e32 v12, v4, v12
	s_nop 0
	v_mul_f32_e32 v12, v14, v12
	s_nop 0
	v_mul_f32_e32 v10, v10, v12
	v_cvt_pk_bf16_f32 v10, v10, s0
	global_store_short v[0:1], v10, off
	v_mul_f32_e32 v10, 0xbfb8aa3b, v16
	v_exp_f32_e32 v10, v10
	s_nop 0
	v_add_f32_e32 v10, 1.0, v10
	v_div_scale_f32 v12, s[0:1], v10, v10, v16
	v_rcp_f32_e32 v13, v12
	s_nop 0
	v_fma_f32 v14, -v12, v13, 1.0
	v_fmac_f32_e32 v13, v14, v13
	v_div_scale_f32 v14, vcc, v16, v10, v16
	v_mul_f32_e32 v29, v14, v13
	v_fma_f32 v30, -v12, v29, v14
	v_fmac_f32_e32 v29, v30, v13
	v_fma_f32 v12, -v12, v29, v14
	v_div_fmas_f32 v12, v12, v13, v29
	v_div_fixup_f32 v10, v12, v10, v16
	s_nop 0
	v_sub_f32_e32 v12, v27, v2
	s_nop 0
	v_mul_f32_e32 v12, v4, v12
	s_nop 0
	v_mul_f32_e32 v12, v17, v12
	s_nop 0
	v_mul_f32_e32 v10, v10, v12
	v_cvt_pk_bf16_f32 v10, v10, s0
	global_store_short v[0:1], v10, off offset:32
	v_mul_f32_e32 v10, 0xbfb8aa3b, v18
	v_exp_f32_e32 v10, v10
	s_nop 0
	v_add_f32_e32 v10, 1.0, v10
	v_div_scale_f32 v12, s[0:1], v10, v10, v18
	v_rcp_f32_e32 v13, v12
	s_nop 0
	v_fma_f32 v14, -v12, v13, 1.0
	v_fmac_f32_e32 v13, v14, v13
	v_div_scale_f32 v14, vcc, v18, v10, v18
	v_mul_f32_e32 v16, v14, v13
	v_fma_f32 v17, -v12, v16, v14
	v_fmac_f32_e32 v16, v17, v13
	v_fma_f32 v12, -v12, v16, v14
	v_div_fmas_f32 v12, v12, v13, v16
	v_div_fixup_f32 v10, v12, v10, v18
	s_nop 0
	v_sub_f32_e32 v12, v23, v2
	s_nop 0
	v_mul_f32_e32 v12, v4, v12
	s_nop 0
	v_mul_f32_e32 v12, v20, v12
	s_nop 0
	v_mul_f32_e32 v10, v10, v12
	v_cvt_pk_bf16_f32 v10, v10, s0
	global_store_short v[0:1], v10, off offset:64
	v_mul_f32_e32 v10, 0xbfb8aa3b, v21
	v_exp_f32_e32 v10, v10
	s_nop 0
	v_add_f32_e32 v10, 1.0, v10
	v_div_scale_f32 v12, s[0:1], v10, v10, v21
	v_rcp_f32_e32 v13, v12
	s_nop 0
	v_fma_f32 v14, -v12, v13, 1.0
	v_fmac_f32_e32 v13, v14, v13
	v_div_scale_f32 v14, vcc, v21, v10, v21
	v_mul_f32_e32 v16, v14, v13
	v_fma_f32 v17, -v12, v16, v14
	v_fmac_f32_e32 v16, v17, v13
	v_fma_f32 v12, -v12, v16, v14
	v_div_fmas_f32 v12, v12, v13, v16
	v_div_fixup_f32 v10, v12, v10, v21
	s_nop 0
	v_sub_f32_e32 v12, v19, v2
	s_nop 0
	v_mul_f32_e32 v12, v4, v12
	s_nop 0
	v_mul_f32_e32 v12, v22, v12
	s_nop 0
	v_mul_f32_e32 v10, v10, v12
	v_cvt_pk_bf16_f32 v10, v10, s0
	global_store_short v[0:1], v10, off offset:96
	v_mul_f32_e32 v10, 0xbfb8aa3b, v24
	v_exp_f32_e32 v10, v10
	s_nop 0
	v_add_f32_e32 v10, 1.0, v10
	v_div_scale_f32 v12, s[0:1], v10, v10, v24
	v_rcp_f32_e32 v13, v12
	s_nop 0
	v_fma_f32 v14, -v12, v13, 1.0
	v_fmac_f32_e32 v13, v14, v13
	v_div_scale_f32 v14, vcc, v24, v10, v24
	v_mul_f32_e32 v16, v14, v13
	v_fma_f32 v17, -v12, v16, v14
	v_fmac_f32_e32 v16, v17, v13
	v_fma_f32 v12, -v12, v16, v14
	v_div_fmas_f32 v12, v12, v13, v16
	v_div_fixup_f32 v10, v12, v10, v24
	s_nop 0
	v_sub_f32_e32 v12, v15, v2
	s_nop 0
	v_mul_f32_e32 v12, v4, v12
	s_nop 0
	v_mul_f32_e32 v12, v25, v12
	s_nop 0
	v_mul_f32_e32 v10, v10, v12
	v_cvt_pk_bf16_f32 v10, v10, s0
	global_store_short v[0:1], v10, off offset:128
	v_mul_f32_e32 v10, 0xbfb8aa3b, v26
	v_exp_f32_e32 v10, v10
	s_nop 0
	v_add_f32_e32 v10, 1.0, v10
	v_div_scale_f32 v12, s[0:1], v10, v10, v26
	v_rcp_f32_e32 v13, v12
	s_nop 0
	v_fma_f32 v14, -v12, v13, 1.0
	v_fmac_f32_e32 v13, v14, v13
	v_div_scale_f32 v14, vcc, v26, v10, v26
	v_mul_f32_e32 v15, v14, v13
	v_fma_f32 v16, -v12, v15, v14
	v_fmac_f32_e32 v15, v16, v13
	v_fma_f32 v12, -v12, v15, v14
	v_div_fmas_f32 v12, v12, v13, v15
	v_div_fixup_f32 v10, v12, v10, v26
	s_nop 0
	v_sub_f32_e32 v11, v11, v2
	s_nop 0
	v_mul_f32_e32 v11, v4, v11
	s_nop 0
	v_mul_f32_e32 v11, v28, v11
	s_nop 0
	v_mul_f32_e32 v10, v10, v11
	v_cvt_pk_bf16_f32 v10, v10, s0
	global_store_short v[0:1], v10, off offset:160
	v_mul_f32_e32 v10, 0xbfb8aa3b, v9
	v_exp_f32_e32 v10, v10
	s_nop 0
	v_add_f32_e32 v10, 1.0, v10
	v_div_scale_f32 v11, s[0:1], v10, v10, v9
	v_rcp_f32_e32 v12, v11
	s_nop 0
	v_fma_f32 v13, -v11, v12, 1.0
	v_fmac_f32_e32 v12, v13, v12
	v_div_scale_f32 v13, vcc, v9, v10, v9
	v_mul_f32_e32 v14, v13, v12
	v_fma_f32 v15, -v11, v14, v13
	v_fmac_f32_e32 v14, v15, v12
	v_fma_f32 v11, -v11, v14, v13
	v_div_fmas_f32 v11, v11, v12, v14
	v_div_fixup_f32 v9, v11, v10, v9
	s_nop 0
	v_sub_f32_e32 v7, v7, v2
	s_nop 0
	v_mul_f32_e32 v7, v4, v7
	s_nop 0
	v_mul_f32_e32 v7, v8, v7
	s_nop 0
	v_mul_f32_e32 v7, v9, v7
	v_cvt_pk_bf16_f32 v7, v7, s0
	global_store_short v[0:1], v7, off offset:192
	v_mul_f32_e32 v7, 0xbfb8aa3b, v6
	v_exp_f32_e32 v7, v7
	s_nop 0
	v_add_f32_e32 v7, 1.0, v7
	v_div_scale_f32 v8, s[0:1], v7, v7, v6
	v_rcp_f32_e32 v9, v8
	s_nop 0
	v_fma_f32 v10, -v8, v9, 1.0
	v_fmac_f32_e32 v9, v10, v9
	v_div_scale_f32 v10, vcc, v6, v7, v6
	v_mul_f32_e32 v11, v10, v9
	v_fma_f32 v12, -v8, v11, v10
	v_fmac_f32_e32 v11, v12, v9
	v_fma_f32 v8, -v8, v11, v10
	v_div_fmas_f32 v8, v8, v9, v11
	v_div_fixup_f32 v6, v8, v7, v6
	s_nop 0
	v_sub_f32_e32 v2, v3, v2
	s_nop 0
	v_mul_f32_e32 v2, v4, v2
	s_waitcnt vmcnt(7)
	v_mul_f32_e32 v2, v5, v2
	s_nop 0
	v_mul_f32_e32 v2, v6, v2
	v_cvt_pk_bf16_f32 v2, v2, s0
	global_store_short v[0:1], v2, off offset:224
	s_cbranch_scc1 .LBB0_408
